# conv: five row-pair landing zones (five pairs in flight instead of four)
# speedup vs baseline: 1.0065x; 1.0065x over previous
.LBB0_227:
	s_lshl_b32 s0, s2, 4
	v_or_b32_e32 v86, s0, v102
	v_mad_i64_i32 v[24:25], s[18:19], v86, s6, v[56:57]
	v_add_co_u32_e32 v26, vcc, 0x1000, v24
	global_load_dwordx4 v[52:55], v[24:25], off
	global_load_dwordx4 v[48:51], v[24:25], off offset:3584
	v_addc_co_u32_e32 v27, vcc, 0, v25, vcc
	global_load_dwordx4 v[44:47], v[26:27], off offset:3072
	v_add_co_u32_e32 v26, vcc, s15, v24
	s_bfe_i32 s0, s2, 0x1001b
	s_nop 0
	v_addc_co_u32_e32 v27, vcc, 0, v25, vcc
	global_load_dwordx4 v[40:43], v[26:27], off offset:2560
	v_add_co_u32_e32 v26, vcc, s35, v24
	v_ashrrev_i32_e32 v87, 31, v86
	s_nop 0
	v_addc_co_u32_e32 v27, vcc, 0, v25, vcc
	global_load_dwordx4 v[36:39], v[26:27], off offset:2048
	v_add_co_u32_e32 v26, vcc, s44, v24
	s_lshr_b32 s0, s0, 19
	s_nop 0
	v_addc_co_u32_e32 v27, vcc, 0, v25, vcc
	v_lshlrev_b64 v[84:85], 11, v[86:87]
	global_load_dwordx4 v[32:35], v[26:27], off offset:1536
	v_add_co_u32_e32 v26, vcc, s46, v24
	v_add_u32_e32 v87, s0, v86
	s_nop 0
	v_addc_co_u32_e32 v27, vcc, 0, v25, vcc
	v_and_b32_e32 v87, 0xffffe000, v87
	v_add_co_u32_e32 v24, vcc, s45, v24
	v_sub_u32_e32 v87, v86, v87
	s_nop 0
	v_addc_co_u32_e32 v25, vcc, 0, v25, vcc
	v_add_u32_e32 v217, -1, v87
	v_cmp_gt_u32_e32 vcc, s15, v217
	global_load_dwordx4 v[28:31], v[26:27], off offset:1024
	v_lshl_add_u64 v[84:85], v[58:59], 0, v[84:85]
	global_load_dwordx4 v[24:27], v[24:25], off offset:512
	s_nop 0
	v_add_u32_e32 v88, -1, v86
	v_max_i32_e32 v88, 0, v88
	v_min_u32_e32 v88, 0xffff, v88
	v_mul_u32_u24_e32 v208, 0xe00, v88
	v_lshl_add_u64 v[92:93], v[56:57], 0, v[208:209]
	global_load_dwordx4 v[88:91], v[92:93], off offset:512
	s_nop 0
	global_load_dwordx4 v[92:95], v[92:93], off offset:1024
	v_add_u32_e32 v218, 0, v86
	v_max_i32_e32 v218, 0, v218
	v_min_u32_e32 v218, 0xffff, v218
	v_mul_u32_u24_e32 v208, 0xe00, v218
	v_lshl_add_u64 v[222:223], v[56:57], 0, v[208:209]
	global_load_dwordx4 v[218:221], v[222:223], off offset:512
	s_nop 0
	global_load_dwordx4 v[222:225], v[222:223], off offset:1024
	v_add_u32_e32 v226, 1, v86
	v_max_i32_e32 v226, 0, v226
	v_min_u32_e32 v226, 0xffff, v226
	v_mul_u32_u24_e32 v208, 0xe00, v226
	v_lshl_add_u64 v[230:231], v[56:57], 0, v[208:209]
	global_load_dwordx4 v[226:229], v[230:231], off offset:512
	s_nop 0
	global_load_dwordx4 v[230:233], v[230:231], off offset:1024
	v_add_u32_e32 v234, 2, v86
	v_max_i32_e32 v234, 0, v234
	v_min_u32_e32 v234, 0xffff, v234
	v_mul_u32_u24_e32 v208, 0xe00, v234
	v_lshl_add_u64 v[238:239], v[56:57], 0, v[208:209]
	global_load_dwordx4 v[234:237], v[238:239], off offset:512
	s_nop 0
	global_load_dwordx4 v[238:241], v[238:239], off offset:1024
	v_add_u32_e32 v246, 3, v86
	v_max_i32_e32 v246, 0, v246
	v_min_u32_e32 v246, 0xffff, v246
	v_mul_u32_u24_e32 v208, 0xe00, v246
	v_lshl_add_u64 v[104:105], v[56:57], 0, v[208:209]
	global_load_dwordx4 v[246:249], v[104:105], off offset:512
	s_nop 0
	global_load_dwordx4 v[104:107], v[104:105], off offset:1024
	s_add_i32 s2, s2, s3
	s_cmpk_lt_i32 s2, 0x1000
	s_waitcnt vmcnt(8)
	v_cndmask_b32_e32 v97, 0, v88, vcc
	v_cndmask_b32_e32 v149, 0, v93, vcc
	v_cndmask_b32_e32 v98, 0, v92, vcc
	v_cndmask_b32_e32 v141, 0, v91, vcc
	v_cndmask_b32_e32 v143, 0, v90, vcc
	v_cndmask_b32_e32 v96, 0, v89, vcc
	v_cndmask_b32_e32 v145, 0, v95, vcc
	v_cndmask_b32_e32 v147, 0, v94, vcc
	v_add_u32_e32 v88, 4, v86
	v_max_i32_e32 v88, 0, v88
	v_min_u32_e32 v88, 0xffff, v88
	v_mul_u32_u24_e32 v208, 0xe00, v88
	v_lshl_add_u64 v[92:93], v[56:57], 0, v[208:209]
	global_load_dwordx4 v[88:91], v[92:93], off offset:512
	s_nop 0
	global_load_dwordx4 v[92:95], v[92:93], off offset:1024
	v_cmp_lt_i32_e32 vcc, -1, v87
	v_add_u32_e32 v87, 8, v87
	v_and_b32_e32 v186, 0xffff0000, v145
	s_waitcnt vmcnt(8)
	v_cndmask_b32_e32 v146, 0, v218, vcc
	v_cndmask_b32_e32 v152, 0, v223, vcc
	v_cndmask_b32_e32 v144, 0, v222, vcc
	v_cndmask_b32_e32 v99, 0, v221, vcc
	v_cndmask_b32_e32 v100, 0, v220, vcc
	v_cndmask_b32_e32 v101, 0, v219, vcc
	v_cndmask_b32_e32 v151, 0, v225, vcc
	v_cndmask_b32_e32 v153, 0, v224, vcc
	v_add_u32_e32 v218, 5, v86
	v_max_i32_e32 v218, 0, v218
	v_min_u32_e32 v218, 0xffff, v218
	v_mul_u32_u24_e32 v208, 0xe00, v218
	v_lshl_add_u64 v[222:223], v[56:57], 0, v[208:209]
	global_load_dwordx4 v[218:221], v[222:223], off offset:512
	s_nop 0
	global_load_dwordx4 v[222:225], v[222:223], off offset:1024
	v_lshlrev_b32_e32 v150, 16, v101
	v_and_b32_e32 v154, 0xffff0000, v101
	v_lshlrev_b32_e32 v158, 16, v100
	v_and_b32_e32 v162, 0xffff0000, v100
	v_lshlrev_b32_e32 v166, 16, v99
	v_and_b32_e32 v170, 0xffff0000, v99
	v_lshlrev_b32_e32 v140, 16, v144
	v_lshlrev_b32_e32 v142, 16, v146
	v_and_b32_e32 v144, 0xffff0000, v144
	v_and_b32_e32 v146, 0xffff0000, v146
	v_lshlrev_b32_e32 v148, 16, v152
	v_and_b32_e32 v152, 0xffff0000, v152
	v_lshlrev_b32_e32 v156, 16, v153
	v_and_b32_e32 v160, 0xffff0000, v153
	v_lshlrev_b32_e32 v164, 16, v151
	v_and_b32_e32 v168, 0xffff0000, v151
	s_waitcnt vmcnt(8)
	v_cndmask_b32_e32 v161, 0, v226, vcc
	v_cndmask_b32_e32 v167, 0, v231, vcc
	v_cndmask_b32_e32 v169, 0, v230, vcc
	v_cndmask_b32_e32 v155, 0, v229, vcc
	v_cndmask_b32_e32 v157, 0, v228, vcc
	v_cndmask_b32_e32 v159, 0, v227, vcc
	v_cndmask_b32_e32 v163, 0, v233, vcc
	v_cndmask_b32_e32 v165, 0, v232, vcc
	v_add_u32_e32 v226, 6, v86
	v_max_i32_e32 v226, 0, v226
	v_min_u32_e32 v226, 0xffff, v226
	v_mul_u32_u24_e32 v208, 0xe00, v226
	v_lshl_add_u64 v[230:231], v[56:57], 0, v[208:209]
	global_load_dwordx4 v[226:229], v[230:231], off offset:512
	s_nop 0
	global_load_dwordx4 v[230:233], v[230:231], off offset:1024
	v_and_b32_e32 v187, 0xffff0000, v163
	s_waitcnt vmcnt(8)
	v_cndmask_b32_e32 v190, 0, v234, vcc
	v_cndmask_b32_e32 v193, 0, v239, vcc
	v_cndmask_b32_e32 v194, 0, v238, vcc
	v_cndmask_b32_e32 v171, 0, v237, vcc
	v_cndmask_b32_e32 v188, 0, v236, vcc
	v_cndmask_b32_e32 v189, 0, v235, vcc
	v_cndmask_b32_e32 v191, 0, v241, vcc
	v_cndmask_b32_e32 v192, 0, v240, vcc
	v_add_u32_e32 v234, 7, v86
	v_max_i32_e32 v234, 0, v234
	v_min_u32_e32 v234, 0xffff, v234
	v_mul_u32_u24_e32 v208, 0xe00, v234
	v_lshl_add_u64 v[238:239], v[56:57], 0, v[208:209]
	global_load_dwordx4 v[234:237], v[238:239], off offset:512
	s_nop 0
	global_load_dwordx4 v[238:241], v[238:239], off offset:1024
	v_lshlrev_b32_e32 v151, 16, v189
	v_and_b32_e32 v153, 0xffff0000, v193
	s_waitcnt vmcnt(8)
	v_cndmask_b32_e32 v198, 0, v246, vcc
	v_cndmask_b32_e32 v201, 0, v105, vcc
	v_cndmask_b32_e32 v202, 0, v104, vcc
	v_cndmask_b32_e32 v195, 0, v249, vcc
	v_cndmask_b32_e32 v196, 0, v248, vcc
	v_cndmask_b32_e32 v197, 0, v247, vcc
	v_cndmask_b32_e32 v199, 0, v107, vcc
	v_cndmask_b32_e32 v200, 0, v106, vcc
	v_add_u32_e32 v246, 8, v86
	v_max_i32_e32 v246, 0, v246
	v_min_u32_e32 v246, 0xffff, v246
	v_mul_u32_u24_e32 v208, 0xe00, v246
	v_lshl_add_u64 v[104:105], v[56:57], 0, v[208:209]
	global_load_dwordx4 v[246:249], v[104:105], off offset:512
	s_nop 0
	global_load_dwordx4 v[104:107], v[104:105], off offset:1024
	s_waitcnt vmcnt(8)
	v_cndmask_b32_e32 v206, 0, v88, vcc
	v_cndmask_b32_e32 v215, 0, v93, vcc
	v_cndmask_b32_e32 v216, 0, v92, vcc
	v_cndmask_b32_e32 v203, 0, v91, vcc
	v_cndmask_b32_e32 v204, 0, v90, vcc
	v_cndmask_b32_e32 v205, 0, v89, vcc
	v_cndmask_b32_e32 v207, 0, v95, vcc
	v_cndmask_b32_e32 v214, 0, v94, vcc
	s_waitcnt vmcnt(6)
	v_cndmask_b32_e32 v136, 0, v218, vcc
	v_cndmask_b32_e32 v137, 0, v223, vcc
	v_cndmask_b32_e32 v139, 0, v222, vcc
	v_cndmask_b32_e32 v124, 0, v221, vcc
	v_cndmask_b32_e32 v126, 0, v220, vcc
	v_cndmask_b32_e32 v132, 0, v219, vcc
	v_cndmask_b32_e32 v127, 0, v225, vcc
	v_cndmask_b32_e32 v133, 0, v224, vcc
	s_waitcnt vmcnt(4)
	v_cndmask_b32_e32 v138, 0, v226, vcc
	v_cndmask_b32_e32 v130, 0, v231, vcc
	v_cndmask_b32_e32 v134, 0, v230, vcc
	v_cndmask_b32_e32 v129, 0, v229, vcc
	v_cndmask_b32_e32 v131, 0, v228, vcc
	v_cndmask_b32_e32 v135, 0, v227, vcc
	v_cndmask_b32_e32 v125, 0, v233, vcc
	v_cndmask_b32_e32 v128, 0, v232, vcc
	s_waitcnt vmcnt(2)
	v_cndmask_b32_e32 v108, 0, v237, vcc
	v_cndmask_b32_e32 v110, 0, v236, vcc
	v_cndmask_b32_e32 v115, 0, v235, vcc
	v_cndmask_b32_e32 v120, 0, v234, vcc
	v_cndmask_b32_e32 v111, 0, v241, vcc
	v_cndmask_b32_e32 v116, 0, v240, vcc
	v_cndmask_b32_e32 v121, 0, v239, vcc
	v_cndmask_b32_e32 v123, 0, v238, vcc
	v_cmp_gt_u32_e32 vcc, s15, v87
	v_lshlrev_b32_e32 v208, 16, v52
	v_and_b32_e32 v52, 0xffff0000, v52
	s_waitcnt vmcnt(0)
	v_cndmask_b32_e32 v113, 0, v249, vcc
	v_cndmask_b32_e32 v117, 0, v248, vcc
	v_cndmask_b32_e32 v119, 0, v247, vcc
	v_cndmask_b32_e32 v122, 0, v246, vcc
	v_lshlrev_b32_e32 v86, 16, v97
	v_lshlrev_b32_e32 v87, 16, v161
	v_lshlrev_b32_e32 v88, 16, v98
	v_lshlrev_b32_e32 v89, 16, v169
	v_pk_mul_f32 v[100:101], v[86:87], v[88:89]
	v_and_b32_e32 v87, 0xffff0000, v161
	v_and_b32_e32 v86, 0xffff0000, v97
	v_and_b32_e32 v89, 0xffff0000, v169
	v_and_b32_e32 v88, 0xffff0000, v98
	v_pk_mul_f32 v[98:99], v[86:87], v[88:89]
	v_lshlrev_b32_e32 v86, 16, v96
	v_lshlrev_b32_e32 v87, 16, v159
	v_lshlrev_b32_e32 v88, 16, v149
	v_lshlrev_b32_e32 v89, 16, v167
	v_pk_mul_f32 v[94:95], v[86:87], v[88:89]
	v_and_b32_e32 v87, 0xffff0000, v159
	v_and_b32_e32 v86, 0xffff0000, v96
	v_and_b32_e32 v89, 0xffff0000, v167
	v_and_b32_e32 v88, 0xffff0000, v149
	v_pk_mul_f32 v[96:97], v[86:87], v[88:89]
	v_lshlrev_b32_e32 v86, 16, v143
	v_lshlrev_b32_e32 v87, 16, v157
	v_lshlrev_b32_e32 v88, 16, v147
	v_lshlrev_b32_e32 v89, 16, v165
	v_cndmask_b32_e32 v114, 0, v105, vcc
	v_cndmask_b32_e32 v118, 0, v104, vcc
	v_pk_mul_f32 v[90:91], v[86:87], v[88:89]
	v_and_b32_e32 v87, 0xffff0000, v157
	v_and_b32_e32 v86, 0xffff0000, v143
	v_and_b32_e32 v89, 0xffff0000, v165
	v_and_b32_e32 v88, 0xffff0000, v147
	v_cndmask_b32_e32 v109, 0, v107, vcc
	v_cndmask_b32_e32 v112, 0, v106, vcc
	v_pk_mul_f32 v[92:93], v[86:87], v[88:89]
	v_lshlrev_b32_e32 v86, 16, v141
	v_lshlrev_b32_e32 v87, 16, v155
	v_lshlrev_b32_e32 v88, 16, v145
	v_lshlrev_b32_e32 v89, 16, v163
	v_pk_mul_f32 v[86:87], v[86:87], v[88:89]
	v_and_b32_e32 v88, 0xffff0000, v141
	v_lshlrev_b32_e32 v143, 16, v190
	v_lshlrev_b32_e32 v141, 16, v194
	v_pk_mul_f32 v[172:173], v[60:61], v[100:101]
	v_pk_mul_f32 v[140:141], v[140:141], v[142:143]
	v_and_b32_e32 v147, 0xffff0000, v190
	v_fma_f32 v142, v8, v140, v172
	v_add_f32_e32 v142, v142, v173
	v_mul_f32_e32 v172, v142, v208
	v_pk_mul_f32 v[142:143], v[60:61], v[140:141]
	v_and_b32_e32 v145, 0xffff0000, v194
	v_fma_f32 v140, v8, v101, v142
	v_pk_mul_f32 v[174:175], v[4:5], v[98:99]
	v_add_f32_e32 v140, v140, v143
	v_pk_mul_f32 v[142:143], v[144:145], v[146:147]
	v_and_b32_e32 v89, 0xffff0000, v155
	v_fma_f32 v144, v9, v142, v174
	v_add_f32_e32 v144, v144, v175
	v_mul_f32_e32 v173, v144, v52
	v_pk_mul_f32 v[144:145], v[4:5], v[142:143]
	v_and_b32_e32 v155, 0xffff0000, v189
	v_lshlrev_b32_e32 v149, 16, v193
	v_fma_f32 v52, v9, v99, v144
	v_pk_mul_f32 v[176:177], v[66:67], v[94:95]
	v_pk_mul_f32 v[178:179], v[6:7], v[96:97]
	v_lshlrev_b32_e32 v159, 16, v188
	v_and_b32_e32 v163, 0xffff0000, v188
	v_lshlrev_b32_e32 v188, 16, v48
	v_and_b32_e32 v48, 0xffff0000, v48
	v_add_f32_e32 v52, v52, v145
	v_pk_mul_f32 v[144:145], v[148:149], v[150:151]
	v_pk_mul_f32 v[148:149], v[152:153], v[154:155]
	v_mul_f32_e32 v142, v52, v48
	v_and_b32_e32 v151, 0xffff0000, v53
	v_lshlrev_b32_e32 v150, 16, v53
	v_mov_b32_e32 v52, v144
	v_mov_b32_e32 v53, v148
	v_mov_b32_e32 v152, v176
	v_mov_b32_e32 v153, v178
	v_pk_fma_f32 v[52:53], v[10:11], v[52:53], v[152:153]
	v_mov_b32_e32 v178, v177
	v_pk_add_f32 v[52:53], v[52:53], v[178:179]
	v_mul_f32_e32 v174, v173, v173
	v_pk_mul_f32 v[52:53], v[52:53], v[150:151]
	v_fmac_f32_e32 v174, v172, v172
	v_pk_mul_f32 v[150:151], v[52:53], v[52:53]
	v_pk_mul_f32 v[146:147], v[66:67], v[144:145]
	v_add_f32_e32 v48, v150, v174
	v_add_f32_e32 v144, v151, v48
	v_pk_mul_f32 v[150:151], v[6:7], v[148:149]
	v_and_b32_e32 v153, 0xffff0000, v49
	v_lshlrev_b32_e32 v152, 16, v49
	v_mov_b32_e32 v48, v95
	v_mov_b32_e32 v49, v97
	v_mov_b32_e32 v154, v146
	v_mov_b32_e32 v155, v150
	v_pk_fma_f32 v[48:49], v[10:11], v[48:49], v[154:155]
	v_mov_b32_e32 v150, v147
	v_lshlrev_b32_e32 v157, 16, v192
	v_and_b32_e32 v161, 0xffff0000, v192
	v_pk_add_f32 v[48:49], v[48:49], v[150:151]
	v_pk_mul_f32 v[180:181], v[72:73], v[90:91]
	v_pk_mul_f32 v[182:183], v[16:17], v[92:93]
	v_pk_mul_f32 v[146:147], v[48:49], v[152:153]
	v_pk_mul_f32 v[150:151], v[156:157], v[158:159]
	v_pk_mul_f32 v[152:153], v[160:161], v[162:163]
	v_mov_b32_e32 v156, v150
	v_mov_b32_e32 v157, v152
	v_mov_b32_e32 v158, v180
	v_mov_b32_e32 v159, v182
	v_pk_fma_f32 v[156:157], v[20:21], v[156:157], v[158:159]
	v_mov_b32_e32 v182, v181
	v_and_b32_e32 v155, 0xffff0000, v54
	v_lshlrev_b32_e32 v154, 16, v54
	v_pk_add_f32 v[156:157], v[156:157], v[182:183]
	v_mul_f32_e32 v140, v140, v188
	v_mul_f32_e32 v175, v142, v142
	v_pk_mul_f32 v[154:155], v[156:157], v[154:155]
	v_fmac_f32_e32 v175, v140, v140
	v_pk_mul_f32 v[48:49], v[146:147], v[146:147]
	v_pk_mul_f32 v[156:157], v[154:155], v[154:155]
	v_add_f32_e32 v48, v48, v175
	v_add_f32_e32 v54, v156, v144
	v_add_f32_e32 v148, v49, v48
	v_pk_mul_f32 v[48:49], v[72:73], v[150:151]
	v_add_f32_e32 v144, v157, v54
	v_pk_mul_f32 v[156:157], v[16:17], v[152:153]
	v_mov_b32_e32 v160, v91
	v_mov_b32_e32 v161, v93
	v_mov_b32_e32 v162, v48
	v_mov_b32_e32 v163, v156
	v_pk_fma_f32 v[160:161], v[20:21], v[160:161], v[162:163]
	v_mov_b32_e32 v156, v49
	v_and_b32_e32 v159, 0xffff0000, v50
	v_lshlrev_b32_e32 v158, 16, v50
	v_pk_add_f32 v[48:49], v[160:161], v[156:157]
	v_pk_mul_f32 v[88:89], v[88:89], v[186:187]
	v_pk_mul_f32 v[156:157], v[48:49], v[158:159]
	v_lshlrev_b32_e32 v167, 16, v171
	v_pk_mul_f32 v[48:49], v[156:157], v[156:157]
	v_and_b32_e32 v171, 0xffff0000, v171
	v_lshlrev_b32_e32 v165, 16, v191
	v_and_b32_e32 v169, 0xffff0000, v191
	v_add_f32_e32 v48, v48, v148
	v_pk_mul_f32 v[184:185], v[78:79], v[86:87]
	v_pk_mul_f32 v[186:187], v[18:19], v[88:89]
	v_add_f32_e32 v148, v49, v48
	v_pk_mul_f32 v[158:159], v[164:165], v[166:167]
	v_pk_mul_f32 v[48:49], v[168:169], v[170:171]
	v_and_b32_e32 v163, 0xffff0000, v55
	v_lshlrev_b32_e32 v162, 16, v55
	v_mov_b32_e32 v54, v158
	v_mov_b32_e32 v55, v48
	v_mov_b32_e32 v164, v184
	v_mov_b32_e32 v165, v186
	v_pk_fma_f32 v[54:55], v[22:23], v[54:55], v[164:165]
	v_mov_b32_e32 v186, v185
	v_pk_add_f32 v[54:55], v[54:55], v[186:187]
	v_pk_mul_f32 v[160:161], v[78:79], v[158:159]
	v_pk_mul_f32 v[54:55], v[54:55], v[162:163]
	v_lshlrev_b32_e32 v164, 16, v200
	v_pk_mul_f32 v[162:163], v[54:55], v[54:55]
	v_lshlrev_b32_e32 v166, 16, v196
	v_add_f32_e32 v50, v162, v144
	v_add_f32_e32 v50, v163, v50
	v_and_b32_e32 v162, 0xffff0000, v197
	v_and_b32_e32 v163, 0xffff0000, v205
	v_lshlrev_b32_e32 v167, 16, v204
	v_lshlrev_b32_e32 v165, 16, v214
	s_waitcnt lgkmcnt(0)
	s_nop 1
	v_add_f32_dpp v50, v50, v50 quad_perm:[1,0,3,2] row_mask:0xf bank_mask:0xf
	v_and_b32_e32 v168, 0xffff0000, v200
	v_and_b32_e32 v170, 0xffff0000, v196
	v_and_b32_e32 v171, 0xffff0000, v204
	v_and_b32_e32 v169, 0xffff0000, v214
	s_waitcnt lgkmcnt(0)
	s_nop 1
	v_add_f32_dpp v50, v50, v50 quad_perm:[2,3,0,1] row_mask:0xf bank_mask:0xf
	v_lshlrev_b32_e32 v174, 16, v195
	v_lshlrev_b32_e32 v175, 16, v203
	v_and_b32_e32 v176, 0xffff0000, v199
	v_and_b32_e32 v178, 0xffff0000, v195
	s_waitcnt lgkmcnt(0)
	s_nop 1
	v_add_f32_dpp v50, v50, v50 row_half_mirror row_mask:0xf bank_mask:0xf
	v_and_b32_e32 v179, 0xffff0000, v203
	v_and_b32_e32 v177, 0xffff0000, v207
	s_waitcnt lgkmcnt(0)
	s_nop 1
	v_add_f32_dpp v50, v50, v50 row_mirror row_mask:0xf bank_mask:0xf
	s_nop 1
	v_mov_b32_e32 v144, v50
	s_nop 1
	v_permlane16_swap_b32_e32 v144, v50
	s_waitcnt lgkmcnt(0)
	v_add_f32_e32 v50, v50, v144
	v_fmamk_f32 v50, v50, 0x3b800000, v244
	v_cmp_gt_f32_e32 vcc, s7, v50
	v_mul_f32_e32 v144, 0x4b800000, v50
	s_nop 0
	v_cndmask_b32_e32 v50, v50, v144, vcc
	v_rsq_f32_e32 v50, v50
	s_nop 0
	v_mul_f32_e32 v144, 0x45800000, v50
	v_cndmask_b32_e32 v50, v50, v144, vcc
	v_mul_f32_e32 v53, v53, v50
	v_mul_f32_e32 v144, v172, v50
	v_mul_f32_e32 v150, v173, v50
	v_mul_f32_e32 v152, v52, v50
	v_cvt_pk_bf16_f32 v52, v144, v150
	v_cvt_pk_bf16_f32 v53, v152, v53
	v_mul_f32_e32 v154, v154, v50
	v_mul_f32_e32 v155, v155, v50
	v_mul_f32_e32 v158, v54, v50
	v_mul_f32_e32 v50, v55, v50
	v_cvt_pk_bf16_f32 v54, v154, v155
	v_cvt_pk_bf16_f32 v55, v158, v50
	global_store_dwordx4 v[84:85], v[52:55], off sc1
	v_mov_b32_e32 v50, v87
	v_mov_b32_e32 v154, v160
	v_pk_mul_f32 v[52:53], v[18:19], v[48:49]
	v_and_b32_e32 v55, 0xffff0000, v51
	v_lshlrev_b32_e32 v54, 16, v51
	v_mov_b32_e32 v51, v89
	v_mov_b32_e32 v155, v52
	v_pk_fma_f32 v[50:51], v[22:23], v[50:51], v[154:155]
	v_mov_b32_e32 v52, v161
	v_pk_add_f32 v[50:51], v[50:51], v[52:53]
	v_lshlrev_b32_e32 v154, 16, v201
	v_pk_mul_f32 v[50:51], v[50:51], v[54:55]
	v_lshlrev_b32_e32 v155, 16, v215
	v_pk_mul_f32 v[52:53], v[50:51], v[50:51]
	v_and_b32_e32 v160, 0xffff0000, v201
	v_add_f32_e32 v48, v52, v148
	v_add_f32_e32 v48, v53, v48
	v_and_b32_e32 v161, 0xffff0000, v215
	v_mov_b32_e32 v148, v145
	v_mov_b32_e32 v152, v151
	v_lshlrev_b32_e32 v172, 16, v199
	s_waitcnt lgkmcnt(0)
	s_nop 1
	v_add_f32_dpp v48, v48, v48 quad_perm:[1,0,3,2] row_mask:0xf bank_mask:0xf
	v_lshlrev_b32_e32 v173, 16, v207
	s_waitcnt lgkmcnt(0)
	s_nop 1
	v_add_f32_dpp v48, v48, v48 quad_perm:[2,3,0,1] row_mask:0xf bank_mask:0xf
	s_waitcnt lgkmcnt(0)
	s_nop 1
	v_add_f32_dpp v48, v48, v48 row_half_mirror row_mask:0xf bank_mask:0xf
	s_waitcnt lgkmcnt(0)
	s_nop 1
	v_add_f32_dpp v48, v48, v48 row_mirror row_mask:0xf bank_mask:0xf
	s_nop 1
	v_mov_b32_e32 v52, v48
	s_nop 1
	v_permlane16_swap_b32_e32 v52, v48
	s_waitcnt lgkmcnt(0)
	v_add_f32_e32 v48, v48, v52
	v_fmamk_f32 v48, v48, 0x3b800000, v244
	v_cmp_gt_f32_e32 vcc, s7, v48
	v_mul_f32_e32 v52, 0x4b800000, v48
	s_nop 0
	v_cndmask_b32_e32 v48, v48, v52, vcc
	v_rsq_f32_e32 v48, v48
	s_nop 0
	v_mul_f32_e32 v52, 0x45800000, v48
	v_cndmask_b32_e32 v48, v48, v52, vcc
	v_mul_f32_e32 v52, v140, v48
	v_mul_f32_e32 v53, v142, v48
	v_mul_f32_e32 v54, v146, v48
	v_mul_f32_e32 v55, v147, v48
	v_mul_f32_e32 v140, v156, v48
	v_mul_f32_e32 v142, v157, v48
	v_mul_f32_e32 v144, v50, v48
	v_mul_f32_e32 v48, v51, v48
	v_cvt_pk_bf16_f32 v50, v52, v53
	v_cvt_pk_bf16_f32 v51, v54, v55
	v_cvt_pk_bf16_f32 v52, v140, v142
	v_cvt_pk_bf16_f32 v53, v144, v48
	global_store_dwordx4 v[84:85], v[50:53], off offset:2048 sc1
	v_lshlrev_b32_e32 v48, 16, v44
	v_and_b32_e32 v54, 0xffff0000, v202
	v_lshlrev_b32_e32 v50, 16, v202
	v_lshlrev_b32_e32 v52, 16, v198
	v_lshlrev_b32_e32 v53, 16, v206
	v_lshlrev_b32_e32 v51, 16, v216
	v_pk_mul_f32 v[180:181], v[50:51], v[52:53]
	v_and_b32_e32 v146, 0xffff0000, v198
	v_pk_mov_b32 v[50:51], v[100:101], v[180:181] op_sel:[1,0]
	v_and_b32_e32 v147, 0xffff0000, v206
	v_pk_mul_f32 v[50:51], v[60:61], v[50:51]
	v_and_b32_e32 v55, 0xffff0000, v216
	v_fma_f32 v50, v8, v141, v50
	v_add_f32_e32 v50, v50, v51
	v_mul_f32_e32 v144, v50, v48
	v_pk_mul_f32 v[50:51], v[62:63], v[180:181]
	v_pk_mul_f32 v[54:55], v[54:55], v[146:147]
	v_fma_f32 v48, v0, v141, v50
	v_add_f32_e32 v48, v48, v51
	v_pk_mov_b32 v[50:51], v[98:99], v[54:55] op_sel:[1,0]
	v_lshlrev_b32_e32 v140, 16, v40
	v_pk_mul_f32 v[50:51], v[4:5], v[50:51]
	v_mul_f32_e32 v150, v48, v140
	v_fma_f32 v48, v9, v143, v50
	v_lshlrev_b32_e32 v156, 16, v197
	v_and_b32_e32 v44, 0xffff0000, v44
	v_lshlrev_b32_e32 v157, 16, v205
	v_add_f32_e32 v48, v48, v51
	v_pk_mul_f32 v[50:51], v[64:65], v[54:55]
	v_mul_f32_e32 v146, v48, v44
	v_fma_f32 v44, v1, v143, v50
	v_pk_mul_f32 v[98:99], v[154:155], v[156:157]
	v_add_f32_e32 v44, v44, v51
	v_pk_mov_b32 v[50:51], v[94:95], v[98:99] op_sel:[1,0]
	v_pk_mul_f32 v[94:95], v[160:161], v[162:163]
	v_and_b32_e32 v40, 0xffff0000, v40
	v_pk_mov_b32 v[96:97], v[96:97], v[94:95] op_sel:[1,0]
	v_pk_mul_f32 v[50:51], v[66:67], v[50:51]
	v_pk_mul_f32 v[96:97], v[6:7], v[96:97]
	v_mul_f32_e32 v147, v44, v40
	v_and_b32_e32 v101, 0xffff0000, v45
	v_lshlrev_b32_e32 v100, 16, v45
	v_mov_b32_e32 v44, v50
	v_mov_b32_e32 v45, v96
	v_pk_fma_f32 v[44:45], v[10:11], v[148:149], v[44:45]
	v_mov_b32_e32 v96, v51
	v_pk_add_f32 v[44:45], v[44:45], v[96:97]
	v_mul_f32_e32 v48, v146, v146
	v_pk_mul_f32 v[44:45], v[44:45], v[100:101]
	v_fmac_f32_e32 v48, v144, v144
	v_pk_mul_f32 v[50:51], v[44:45], v[44:45]
	v_pk_mul_f32 v[52:53], v[68:69], v[98:99]
	v_add_f32_e32 v40, v50, v48
	v_add_f32_e32 v48, v51, v40
	v_pk_mul_f32 v[50:51], v[70:71], v[94:95]
	v_and_b32_e32 v97, 0xffff0000, v41
	v_lshlrev_b32_e32 v96, 16, v41
	v_mov_b32_e32 v40, v52
	v_mov_b32_e32 v41, v50
	v_pk_fma_f32 v[40:41], v[2:3], v[148:149], v[40:41]
	v_mov_b32_e32 v50, v53
	v_pk_add_f32 v[40:41], v[40:41], v[50:51]
	v_mul_f32_e32 v140, v147, v147
	v_pk_mul_f32 v[96:97], v[40:41], v[96:97]
	v_fmac_f32_e32 v140, v150, v150
	v_pk_mul_f32 v[40:41], v[96:97], v[96:97]
	v_pk_mul_f32 v[100:101], v[164:165], v[166:167]
	v_add_f32_e32 v40, v40, v140
	v_add_f32_e32 v142, v41, v40
	v_pk_mov_b32 v[40:41], v[90:91], v[100:101] op_sel:[1,0]
	v_pk_mul_f32 v[90:91], v[168:169], v[170:171]
	v_pk_mul_f32 v[40:41], v[72:73], v[40:41]
	v_pk_mov_b32 v[52:53], v[92:93], v[90:91] op_sel:[1,0]
	v_mov_b32_e32 v140, v40
	v_pk_mul_f32 v[52:53], v[16:17], v[52:53]
	v_and_b32_e32 v93, 0xffff0000, v46
	v_mov_b32_e32 v141, v52
	v_pk_fma_f32 v[140:141], v[20:21], v[152:153], v[140:141]
	v_mov_b32_e32 v52, v41
	v_lshlrev_b32_e32 v92, 16, v46
	v_pk_add_f32 v[40:41], v[140:141], v[52:53]
	v_pk_mul_f32 v[50:51], v[74:75], v[100:101]
	v_pk_mul_f32 v[52:53], v[40:41], v[92:93]
	v_mov_b32_e32 v140, v50
	v_pk_mul_f32 v[40:41], v[52:53], v[52:53]
	v_and_b32_e32 v93, 0xffff0000, v42
	v_add_f32_e32 v40, v40, v48
	v_add_f32_e32 v145, v41, v40
	v_pk_mul_f32 v[40:41], v[76:77], v[90:91]
	v_lshlrev_b32_e32 v92, 16, v42
	v_mov_b32_e32 v141, v40
	v_pk_fma_f32 v[140:141], v[12:13], v[152:153], v[140:141]
	v_mov_b32_e32 v40, v51
	v_pk_add_f32 v[40:41], v[140:141], v[40:41]
	v_pk_mul_f32 v[140:141], v[172:173], v[174:175]
	v_pk_mul_f32 v[92:93], v[40:41], v[92:93]
	v_and_b32_e32 v143, 0xffff0000, v47
	v_pk_mul_f32 v[40:41], v[92:93], v[92:93]
	v_mov_b32_e32 v48, v159
	v_add_f32_e32 v40, v40, v142
	v_add_f32_e32 v148, v41, v40
	v_pk_mov_b32 v[40:41], v[86:87], v[140:141] op_sel:[1,0]
	v_lshlrev_b32_e32 v142, 16, v47
	v_pk_mul_f32 v[50:51], v[78:79], v[40:41]
	v_pk_mul_f32 v[40:41], v[176:177], v[178:179]
	v_mov_b32_e32 v46, v50
	v_pk_mov_b32 v[88:89], v[88:89], v[40:41] op_sel:[1,0]
	v_pk_mul_f32 v[86:87], v[80:81], v[140:141]
	v_pk_mul_f32 v[88:89], v[18:19], v[88:89]
	v_and_b32_e32 v149, 0xffff0000, v129
	v_mov_b32_e32 v47, v88
	v_pk_fma_f32 v[46:47], v[22:23], v[48:49], v[46:47]
	v_mov_b32_e32 v88, v51
	v_pk_add_f32 v[46:47], v[46:47], v[88:89]
	s_nop 0
	v_pk_mul_f32 v[46:47], v[46:47], v[142:143]
	v_lshlrev_b32_e32 v143, 16, v125
	v_pk_mul_f32 v[50:51], v[46:47], v[46:47]
	v_lshlrev_b32_e32 v142, 16, v127
	v_add_f32_e32 v42, v50, v145
	v_add_f32_e32 v42, v51, v42
	v_lshlrev_b32_e32 v145, 16, v129
	s_waitcnt lgkmcnt(0)
	s_nop 1
	v_add_f32_dpp v42, v42, v42 quad_perm:[1,0,3,2] row_mask:0xf bank_mask:0xf
	s_waitcnt lgkmcnt(0)
	s_nop 1
	v_add_f32_dpp v42, v42, v42 quad_perm:[2,3,0,1] row_mask:0xf bank_mask:0xf
	s_waitcnt lgkmcnt(0)
	s_nop 1
	v_add_f32_dpp v42, v42, v42 row_half_mirror row_mask:0xf bank_mask:0xf
	s_waitcnt lgkmcnt(0)
	s_nop 1
	v_add_f32_dpp v42, v42, v42 row_mirror row_mask:0xf bank_mask:0xf
	s_nop 1
	v_mov_b32_e32 v50, v42
	s_nop 1
	v_permlane16_swap_b32_e32 v50, v42
	s_waitcnt lgkmcnt(0)
	v_add_f32_e32 v42, v42, v50
	v_fmamk_f32 v42, v42, 0x3b800000, v244
	v_cmp_gt_f32_e32 vcc, s7, v42
	v_mul_f32_e32 v50, 0x4b800000, v42
	s_nop 0
	v_cndmask_b32_e32 v42, v42, v50, vcc
	v_rsq_f32_e32 v42, v42
	s_nop 0
	v_mul_f32_e32 v50, 0x45800000, v42
	v_cndmask_b32_e32 v42, v42, v50, vcc
	v_add_co_u32_e32 v88, vcc, s34, v84
	v_mul_f32_e32 v50, v144, v42
	v_mul_f32_e32 v51, v146, v42
	v_mul_f32_e32 v44, v44, v42
	v_addc_co_u32_e32 v89, vcc, 0, v85, vcc
	v_mul_f32_e32 v45, v45, v42
	v_mul_f32_e32 v52, v52, v42
	v_mul_f32_e32 v53, v53, v42
	v_mul_f32_e32 v46, v46, v42
	v_cvt_pk_bf16_f32 v50, v50, v51
	v_cvt_pk_bf16_f32 v51, v44, v45
	v_add_co_u32_e32 v44, vcc, s15, v84
	v_mul_f32_e32 v42, v47, v42
	v_cvt_pk_bf16_f32 v52, v52, v53
	v_cvt_pk_bf16_f32 v53, v46, v42
	s_nop 0
	v_addc_co_u32_e32 v45, vcc, 0, v85, vcc
	v_pk_mul_f32 v[46:47], v[82:83], v[40:41]
	global_store_dwordx4 v[44:45], v[50:53], off offset:-4096 sc1
	v_mov_b32_e32 v42, v86
	v_lshlrev_b32_e32 v144, 16, v124
	v_and_b32_e32 v51, 0xffff0000, v43
	v_lshlrev_b32_e32 v50, 16, v43
	v_mov_b32_e32 v43, v46
	v_pk_fma_f32 v[42:43], v[14:15], v[48:49], v[42:43]
	v_mov_b32_e32 v46, v87
	v_pk_add_f32 v[42:43], v[42:43], v[46:47]
	v_lshlrev_b32_e32 v86, 16, v132
	v_pk_mul_f32 v[42:43], v[42:43], v[50:51]
	v_lshlrev_b32_e32 v87, 16, v135
	v_pk_mul_f32 v[46:47], v[42:43], v[42:43]
	v_lshlrev_b32_e32 v53, 16, v130
	v_add_f32_e32 v46, v46, v148
	v_add_f32_e32 v46, v47, v46
	v_and_b32_e32 v148, 0xffff0000, v124
	v_lshlrev_b32_e32 v124, 16, v36
	v_and_b32_e32 v36, 0xffff0000, v36
	v_and_b32_e32 v146, 0xffff0000, v127
	s_waitcnt lgkmcnt(0)
	s_nop 1
	v_add_f32_dpp v46, v46, v46 quad_perm:[1,0,3,2] row_mask:0xf bank_mask:0xf
	v_and_b32_e32 v127, 0xffff0000, v131
	s_waitcnt lgkmcnt(0)
	s_nop 1
	v_add_f32_dpp v46, v46, v46 quad_perm:[2,3,0,1] row_mask:0xf bank_mask:0xf
	s_waitcnt lgkmcnt(0)
	s_nop 1
	v_add_f32_dpp v46, v46, v46 row_half_mirror row_mask:0xf bank_mask:0xf
	s_waitcnt lgkmcnt(0)
	s_nop 1
	v_add_f32_dpp v46, v46, v46 row_mirror row_mask:0xf bank_mask:0xf
	s_nop 1
	v_mov_b32_e32 v47, v46
	s_nop 1
	v_permlane16_swap_b32_e32 v47, v46
	s_waitcnt lgkmcnt(0)
	v_add_f32_e32 v46, v46, v47
	v_fmamk_f32 v46, v46, 0x3b800000, v244
	v_cmp_gt_f32_e32 vcc, s7, v46
	v_mul_f32_e32 v47, 0x4b800000, v46
	s_nop 0
	v_cndmask_b32_e32 v46, v46, v47, vcc
	v_rsq_f32_e32 v46, v46
	s_nop 0
	v_mul_f32_e32 v47, 0x45800000, v46
	v_cndmask_b32_e32 v46, v46, v47, vcc
	v_mul_f32_e32 v47, v150, v46
	v_mul_f32_e32 v48, v147, v46
	v_mul_f32_e32 v49, v96, v46
	v_mul_f32_e32 v50, v97, v46
	v_mul_f32_e32 v51, v92, v46
	v_mul_f32_e32 v52, v93, v46
	v_mul_f32_e32 v42, v42, v46
	v_mul_f32_e32 v43, v43, v46
	v_cvt_pk_bf16_f32 v46, v47, v48
	v_cvt_pk_bf16_f32 v47, v49, v50
	v_cvt_pk_bf16_f32 v48, v51, v52
	v_cvt_pk_bf16_f32 v49, v42, v43
	global_store_dwordx4 v[88:89], v[46:49], off offset:2048 sc1
	v_lshlrev_b32_e32 v42, 16, v139
	v_lshlrev_b32_e32 v43, 16, v134
	v_lshlrev_b32_e32 v46, 16, v136
	v_lshlrev_b32_e32 v47, 16, v138
	v_pk_mul_f32 v[42:43], v[42:43], v[46:47]
	v_mov_b32_e32 v46, v180
	v_mov_b32_e32 v47, v42
	v_pk_mul_f32 v[46:47], v[60:61], v[46:47]
	v_and_b32_e32 v48, 0xffff0000, v139
	v_fma_f32 v46, v8, v181, v46
	v_add_f32_e32 v46, v46, v47
	v_mul_f32_e32 v124, v46, v124
	v_pk_mul_f32 v[46:47], v[62:63], v[42:43]
	v_and_b32_e32 v50, 0xffff0000, v136
	v_fma_f32 v46, v0, v181, v46
	v_and_b32_e32 v51, 0xffff0000, v138
	v_and_b32_e32 v49, 0xffff0000, v134
	v_and_b32_e32 v147, 0xffff0000, v125
	v_lshlrev_b32_e32 v125, 16, v32
	v_add_f32_e32 v46, v46, v47
	v_mul_f32_e32 v125, v46, v125
	v_pk_mul_f32 v[46:47], v[48:49], v[50:51]
	v_mov_b32_e32 v48, v54
	v_mov_b32_e32 v49, v46
	v_pk_mul_f32 v[48:49], v[4:5], v[48:49]
	v_lshlrev_b32_e32 v52, 16, v137
	v_fma_f32 v48, v9, v55, v48
	v_add_f32_e32 v48, v48, v49
	v_and_b32_e32 v88, 0xffff0000, v137
	v_lshlrev_b32_e32 v97, 16, v128
	v_and_b32_e32 v137, 0xffff0000, v128
	v_mul_f32_e32 v128, v48, v36
	v_pk_mul_f32 v[48:49], v[64:65], v[46:47]
	v_and_b32_e32 v92, 0xffff0000, v132
	v_and_b32_e32 v93, 0xffff0000, v135
	v_and_b32_e32 v89, 0xffff0000, v130
	v_fma_f32 v36, v1, v55, v48
	v_add_f32_e32 v36, v36, v49
	v_pk_mul_f32 v[48:49], v[52:53], v[86:87]
	v_pk_mul_f32 v[54:55], v[88:89], v[92:93]
	v_mov_b32_e32 v50, v98
	v_mov_b32_e32 v51, v48
	v_mov_b32_e32 v86, v94
	v_mov_b32_e32 v87, v54
	v_and_b32_e32 v32, 0xffff0000, v32
	v_pk_mul_f32 v[50:51], v[66:67], v[50:51]
	v_pk_mul_f32 v[86:87], v[6:7], v[86:87]
	v_mul_f32_e32 v130, v36, v32
	v_and_b32_e32 v89, 0xffff0000, v37
	v_lshlrev_b32_e32 v88, 16, v37
	v_mov_b32_e32 v94, v99
	v_mov_b32_e32 v36, v50
	v_mov_b32_e32 v37, v86
	v_pk_fma_f32 v[36:37], v[10:11], v[94:95], v[36:37]
	v_mov_b32_e32 v86, v51
	v_pk_add_f32 v[36:37], v[36:37], v[86:87]
	v_mul_f32_e32 v129, v128, v128
	v_pk_mul_f32 v[36:37], v[36:37], v[88:89]
	v_fmac_f32_e32 v129, v124, v124
	v_pk_mul_f32 v[50:51], v[36:37], v[36:37]
	v_pk_mul_f32 v[52:53], v[68:69], v[48:49]
	v_add_f32_e32 v32, v50, v129
	v_add_f32_e32 v98, v51, v32
	v_pk_mul_f32 v[50:51], v[70:71], v[54:55]
	v_and_b32_e32 v87, 0xffff0000, v33
	v_lshlrev_b32_e32 v86, 16, v33
	v_mov_b32_e32 v32, v52
	v_mov_b32_e32 v33, v50
	v_pk_fma_f32 v[32:33], v[2:3], v[94:95], v[32:33]
	v_mov_b32_e32 v50, v53
	v_pk_add_f32 v[32:33], v[32:33], v[50:51]
	v_lshlrev_b32_e32 v96, 16, v133
	v_and_b32_e32 v136, 0xffff0000, v133
	v_lshlrev_b32_e32 v133, 16, v131
	v_mul_f32_e32 v131, v130, v130
	v_pk_mul_f32 v[50:51], v[32:33], v[86:87]
	v_lshlrev_b32_e32 v132, 16, v126
	v_and_b32_e32 v126, 0xffff0000, v126
	v_fmac_f32_e32 v131, v125, v125
	v_pk_mul_f32 v[32:33], v[50:51], v[50:51]
	v_pk_mul_f32 v[52:53], v[96:97], v[132:133]
	v_add_f32_e32 v32, v32, v131
	v_pk_mul_f32 v[88:89], v[136:137], v[126:127]
	v_add_f32_e32 v99, v33, v32
	v_mov_b32_e32 v32, v100
	v_mov_b32_e32 v33, v52
	v_mov_b32_e32 v92, v90
	v_mov_b32_e32 v93, v88
	v_pk_mul_f32 v[32:33], v[72:73], v[32:33]
	v_pk_mul_f32 v[92:93], v[16:17], v[92:93]
	v_mov_b32_e32 v90, v101
	v_mov_b32_e32 v96, v32
	v_mov_b32_e32 v97, v92
	v_pk_fma_f32 v[96:97], v[20:21], v[90:91], v[96:97]
	v_mov_b32_e32 v92, v33
	v_and_b32_e32 v95, 0xffff0000, v38
	v_lshlrev_b32_e32 v94, 16, v38
	v_pk_add_f32 v[32:33], v[96:97], v[92:93]
	v_pk_mul_f32 v[86:87], v[74:75], v[52:53]
	v_pk_mul_f32 v[92:93], v[32:33], v[94:95]
	v_mov_b32_e32 v96, v86
	v_pk_mul_f32 v[32:33], v[92:93], v[92:93]
	v_and_b32_e32 v95, 0xffff0000, v34
	v_add_f32_e32 v32, v32, v98
	v_add_f32_e32 v126, v33, v32
	v_pk_mul_f32 v[32:33], v[76:77], v[88:89]
	v_lshlrev_b32_e32 v94, 16, v34
	v_mov_b32_e32 v97, v32
	v_pk_fma_f32 v[90:91], v[12:13], v[90:91], v[96:97]
	v_mov_b32_e32 v32, v87
	v_pk_add_f32 v[32:33], v[90:91], v[32:33]
	v_pk_mul_f32 v[90:91], v[142:143], v[144:145]
	v_pk_mul_f32 v[86:87], v[32:33], v[94:95]
	v_mov_b32_e32 v98, v40
	v_pk_mul_f32 v[32:33], v[86:87], v[86:87]
	v_and_b32_e32 v101, 0xffff0000, v39
	v_add_f32_e32 v32, v32, v99
	v_add_f32_e32 v127, v33, v32
	v_mov_b32_e32 v32, v140
	v_mov_b32_e32 v33, v90
	v_pk_mul_f32 v[94:95], v[78:79], v[32:33]
	v_pk_mul_f32 v[32:33], v[146:147], v[148:149]
	v_lshlrev_b32_e32 v100, 16, v39
	v_mov_b32_e32 v99, v32
	v_pk_mul_f32 v[98:99], v[18:19], v[98:99]
	v_mov_b32_e32 v40, v141
	v_mov_b32_e32 v38, v94
	v_mov_b32_e32 v39, v98
	v_pk_fma_f32 v[38:39], v[22:23], v[40:41], v[38:39]
	v_mov_b32_e32 v98, v95
	v_pk_add_f32 v[38:39], v[38:39], v[98:99]
	v_pk_mul_f32 v[96:97], v[80:81], v[90:91]
	v_pk_mul_f32 v[38:39], v[38:39], v[100:101]
	v_and_b32_e32 v100, 0xffff0000, v110
	v_pk_mul_f32 v[94:95], v[38:39], v[38:39]
	v_and_b32_e32 v101, 0xffff0000, v117
	v_add_f32_e32 v34, v94, v126
	v_add_f32_e32 v34, v95, v34
	s_waitcnt lgkmcnt(0)
	s_nop 1
	v_add_f32_dpp v34, v34, v34 quad_perm:[1,0,3,2] row_mask:0xf bank_mask:0xf
	s_waitcnt lgkmcnt(0)
	s_nop 1
	v_add_f32_dpp v34, v34, v34 quad_perm:[2,3,0,1] row_mask:0xf bank_mask:0xf
	s_waitcnt lgkmcnt(0)
	s_nop 1
	v_add_f32_dpp v34, v34, v34 row_half_mirror row_mask:0xf bank_mask:0xf
	s_waitcnt lgkmcnt(0)
	s_nop 1
	v_add_f32_dpp v34, v34, v34 row_mirror row_mask:0xf bank_mask:0xf
	s_nop 1
	v_mov_b32_e32 v94, v34
	s_nop 1
	v_permlane16_swap_b32_e32 v94, v34
	s_waitcnt lgkmcnt(0)
	v_add_f32_e32 v34, v34, v94
	v_fmamk_f32 v34, v34, 0x3b800000, v244
	v_cmp_gt_f32_e32 vcc, s7, v34
	v_mul_f32_e32 v94, 0x4b800000, v34
	s_nop 0
	v_cndmask_b32_e32 v34, v34, v94, vcc
	v_rsq_f32_e32 v34, v34
	s_nop 0
	v_mul_f32_e32 v94, 0x45800000, v34
	v_cndmask_b32_e32 v34, v34, v94, vcc
	v_mul_f32_e32 v37, v37, v34
	v_mul_f32_e32 v94, v124, v34
	v_mul_f32_e32 v95, v128, v34
	v_mul_f32_e32 v98, v36, v34
	v_cvt_pk_bf16_f32 v36, v94, v95
	v_cvt_pk_bf16_f32 v37, v98, v37
	v_mul_f32_e32 v92, v92, v34
	v_mul_f32_e32 v93, v93, v34
	v_mul_f32_e32 v99, v38, v34
	v_mul_f32_e32 v34, v39, v34
	v_cvt_pk_bf16_f32 v38, v92, v93
	v_cvt_pk_bf16_f32 v39, v99, v34
	global_store_dwordx4 v[44:45], v[36:39], off sc1
	v_mov_b32_e32 v34, v96
	v_lshlrev_b32_e32 v96, 16, v110
	v_pk_mul_f32 v[36:37], v[82:83], v[32:33]
	v_and_b32_e32 v39, 0xffff0000, v35
	v_lshlrev_b32_e32 v38, 16, v35
	v_mov_b32_e32 v35, v36
	v_pk_fma_f32 v[34:35], v[14:15], v[40:41], v[34:35]
	v_mov_b32_e32 v36, v97
	v_pk_add_f32 v[34:35], v[34:35], v[36:37]
	v_lshlrev_b32_e32 v110, 16, v111
	v_pk_mul_f32 v[34:35], v[34:35], v[38:39]
	v_lshlrev_b32_e32 v94, 16, v116
	v_pk_mul_f32 v[36:37], v[34:35], v[34:35]
	v_and_b32_e32 v98, 0xffff0000, v116
	v_add_f32_e32 v36, v36, v127
	v_add_f32_e32 v36, v37, v36
	v_lshlrev_b32_e32 v116, 16, v108
	v_and_b32_e32 v124, 0xffff0000, v108
	v_lshlrev_b32_e32 v108, 16, v28
	v_and_b32_e32 v28, 0xffff0000, v28
	s_waitcnt lgkmcnt(0)
	s_nop 1
	v_add_f32_dpp v36, v36, v36 quad_perm:[1,0,3,2] row_mask:0xf bank_mask:0xf
	v_and_b32_e32 v92, 0xffff0000, v115
	v_and_b32_e32 v93, 0xffff0000, v119
	v_lshlrev_b32_e32 v95, 16, v112
	v_and_b32_e32 v99, 0xffff0000, v112
	s_waitcnt lgkmcnt(0)
	s_nop 1
	v_add_f32_dpp v36, v36, v36 quad_perm:[2,3,0,1] row_mask:0xf bank_mask:0xf
	v_lshlrev_b32_e32 v97, 16, v117
	v_lshlrev_b32_e32 v117, 16, v113
	s_waitcnt lgkmcnt(0)
	s_nop 1
	v_add_f32_dpp v36, v36, v36 row_half_mirror row_mask:0xf bank_mask:0xf
	s_waitcnt lgkmcnt(0)
	s_nop 1
	v_add_f32_dpp v36, v36, v36 row_mirror row_mask:0xf bank_mask:0xf
	s_nop 1
	v_mov_b32_e32 v37, v36
	s_nop 1
	v_permlane16_swap_b32_e32 v37, v36
	s_waitcnt lgkmcnt(0)
	v_add_f32_e32 v36, v36, v37
	v_fmamk_f32 v36, v36, 0x3b800000, v244
	v_cmp_gt_f32_e32 vcc, s7, v36
	v_mul_f32_e32 v37, 0x4b800000, v36
	s_nop 0
	v_cndmask_b32_e32 v36, v36, v37, vcc
	v_rsq_f32_e32 v36, v36
	s_nop 0
	v_mul_f32_e32 v37, 0x45800000, v36
	v_cndmask_b32_e32 v36, v36, v37, vcc
	v_mul_f32_e32 v37, v125, v36
	v_mul_f32_e32 v38, v130, v36
	v_mul_f32_e32 v39, v50, v36
	v_mul_f32_e32 v40, v51, v36
	v_mul_f32_e32 v41, v86, v36
	v_mul_f32_e32 v50, v87, v36
	v_mul_f32_e32 v51, v34, v36
	v_mul_f32_e32 v86, v35, v36
	v_cvt_pk_bf16_f32 v34, v37, v38
	v_cvt_pk_bf16_f32 v35, v39, v40
	v_cvt_pk_bf16_f32 v36, v41, v50
	v_cvt_pk_bf16_f32 v37, v51, v86
	global_store_dwordx4 v[44:45], v[34:37], off offset:2048 sc1
	v_and_b32_e32 v38, 0xffff0000, v123
	v_and_b32_e32 v40, 0xffff0000, v120
	v_lshlrev_b32_e32 v34, 16, v123
	v_lshlrev_b32_e32 v36, 16, v120
	v_lshlrev_b32_e32 v37, 16, v122
	v_lshlrev_b32_e32 v35, 16, v118
	v_pk_mul_f32 v[34:35], v[34:35], v[36:37]
	v_mov_b32_e32 v36, v42
	v_mov_b32_e32 v37, v34
	v_pk_mul_f32 v[34:35], v[62:63], v[34:35]
	v_pk_mul_f32 v[36:37], v[60:61], v[36:37]
	v_fma_f32 v34, v0, v43, v34
	v_lshlrev_b32_e32 v44, 16, v121
	v_and_b32_e32 v86, 0xffff0000, v121
	v_and_b32_e32 v120, 0xffff0000, v111
	v_and_b32_e32 v41, 0xffff0000, v122
	v_and_b32_e32 v39, 0xffff0000, v118
	v_lshlrev_b32_e32 v111, 16, v109
	v_and_b32_e32 v121, 0xffff0000, v109
	v_lshlrev_b32_e32 v109, 16, v24
	v_fma_f32 v36, v8, v43, v36
	v_add_f32_e32 v34, v34, v35
	v_add_f32_e32 v36, v36, v37
	v_mul_f32_e32 v109, v34, v109
	v_pk_mul_f32 v[34:35], v[38:39], v[40:41]
	v_mul_f32_e32 v108, v36, v108
	v_mov_b32_e32 v36, v46
	v_mov_b32_e32 v37, v34
	v_pk_mul_f32 v[36:37], v[4:5], v[36:37]
	v_pk_mul_f32 v[34:35], v[64:65], v[34:35]
	v_fma_f32 v36, v9, v47, v36
	v_add_f32_e32 v36, v36, v37
	v_lshlrev_b32_e32 v50, 16, v115
	v_lshlrev_b32_e32 v51, 16, v119
	v_lshlrev_b32_e32 v45, 16, v114
	v_and_b32_e32 v87, 0xffff0000, v114
	v_mul_f32_e32 v112, v36, v28
	v_fma_f32 v28, v1, v47, v34
	v_add_f32_e32 v28, v28, v35
	v_pk_mul_f32 v[34:35], v[44:45], v[50:51]
	v_pk_mul_f32 v[38:39], v[86:87], v[92:93]
	v_mov_b32_e32 v36, v48
	v_mov_b32_e32 v37, v34
	v_mov_b32_e32 v40, v54
	v_mov_b32_e32 v41, v38
	v_and_b32_e32 v24, 0xffff0000, v24
	v_pk_mul_f32 v[36:37], v[66:67], v[36:37]
	v_pk_mul_f32 v[40:41], v[6:7], v[40:41]
	v_and_b32_e32 v125, 0xffff0000, v113
	v_mul_f32_e32 v113, v28, v24
	v_and_b32_e32 v43, 0xffff0000, v29
	v_lshlrev_b32_e32 v42, 16, v29
	v_mov_b32_e32 v54, v49
	v_mov_b32_e32 v28, v36
	v_mov_b32_e32 v29, v40
	v_pk_fma_f32 v[28:29], v[10:11], v[54:55], v[28:29]
	v_mov_b32_e32 v40, v37
	v_pk_add_f32 v[28:29], v[28:29], v[40:41]
	v_mul_f32_e32 v46, v112, v112
	v_pk_mul_f32 v[28:29], v[28:29], v[42:43]
	v_fmac_f32_e32 v46, v108, v108
	v_pk_mul_f32 v[36:37], v[28:29], v[28:29]
	v_pk_mul_f32 v[34:35], v[68:69], v[34:35]
	v_add_f32_e32 v24, v36, v46
	v_add_f32_e32 v46, v37, v24
	v_pk_mul_f32 v[36:37], v[70:71], v[38:39]
	v_and_b32_e32 v39, 0xffff0000, v25
	v_lshlrev_b32_e32 v38, 16, v25
	v_mov_b32_e32 v24, v34
	v_mov_b32_e32 v25, v36
	v_pk_fma_f32 v[24:25], v[2:3], v[54:55], v[24:25]
	v_mov_b32_e32 v36, v35
	v_pk_add_f32 v[24:25], v[24:25], v[36:37]
	v_mul_f32_e32 v47, v113, v113
	v_pk_mul_f32 v[24:25], v[24:25], v[38:39]
	v_fmac_f32_e32 v47, v109, v109
	v_pk_mul_f32 v[34:35], v[24:25], v[24:25]
	v_pk_mul_f32 v[38:39], v[98:99], v[100:101]
	v_add_f32_e32 v34, v34, v47
	v_add_f32_e32 v47, v35, v34
	v_pk_mul_f32 v[34:35], v[94:95], v[96:97]
	v_mov_b32_e32 v36, v52
	v_mov_b32_e32 v37, v34
	v_mov_b32_e32 v40, v88
	v_mov_b32_e32 v41, v38
	v_pk_mul_f32 v[36:37], v[72:73], v[36:37]
	v_pk_mul_f32 v[40:41], v[16:17], v[40:41]
	v_mov_b32_e32 v88, v53
	v_mov_b32_e32 v44, v36
	v_mov_b32_e32 v45, v40
	v_pk_fma_f32 v[44:45], v[20:21], v[88:89], v[44:45]
	v_mov_b32_e32 v40, v37
	v_and_b32_e32 v43, 0xffff0000, v30
	v_lshlrev_b32_e32 v42, 16, v30
	v_pk_add_f32 v[36:37], v[44:45], v[40:41]
	v_pk_mul_f32 v[34:35], v[74:75], v[34:35]
	v_pk_mul_f32 v[36:37], v[36:37], v[42:43]
	v_pk_mul_f32 v[38:39], v[76:77], v[38:39]
	v_pk_mul_f32 v[40:41], v[36:37], v[36:37]
	v_mov_b32_e32 v42, v34
	v_mov_b32_e32 v43, v38
	v_add_f32_e32 v30, v40, v46
	v_pk_fma_f32 v[42:43], v[12:13], v[88:89], v[42:43]
	v_mov_b32_e32 v38, v35
	v_add_f32_e32 v48, v41, v30
	v_and_b32_e32 v41, 0xffff0000, v26
	v_lshlrev_b32_e32 v40, 16, v26
	v_pk_add_f32 v[34:35], v[42:43], v[38:39]
	v_pk_mul_f32 v[42:43], v[120:121], v[124:125]
	v_pk_mul_f32 v[34:35], v[34:35], v[40:41]
	v_mov_b32_e32 v40, v90
	v_pk_mul_f32 v[38:39], v[34:35], v[34:35]
	v_mov_b32_e32 v44, v32
	v_add_f32_e32 v26, v38, v47
	v_add_f32_e32 v49, v39, v26
	v_pk_mul_f32 v[38:39], v[110:111], v[116:117]
	v_mov_b32_e32 v45, v42
	v_mov_b32_e32 v41, v38
	v_pk_mul_f32 v[40:41], v[78:79], v[40:41]
	v_pk_mul_f32 v[44:45], v[18:19], v[44:45]
	v_and_b32_e32 v47, 0xffff0000, v31
	v_lshlrev_b32_e32 v46, 16, v31
	v_mov_b32_e32 v32, v91
	v_mov_b32_e32 v30, v40
	v_mov_b32_e32 v31, v44
	v_pk_fma_f32 v[30:31], v[22:23], v[32:33], v[30:31]
	v_mov_b32_e32 v44, v41
	v_pk_add_f32 v[30:31], v[30:31], v[44:45]
	v_pk_mul_f32 v[38:39], v[80:81], v[38:39]
	v_pk_mul_f32 v[30:31], v[30:31], v[46:47]
	s_nop 0
	v_pk_mul_f32 v[40:41], v[30:31], v[30:31]
	s_nop 0
	v_add_f32_e32 v26, v40, v48
	v_add_f32_e32 v26, v41, v26
	s_waitcnt lgkmcnt(0)
	s_nop 1
	v_add_f32_dpp v26, v26, v26 quad_perm:[1,0,3,2] row_mask:0xf bank_mask:0xf
	s_waitcnt lgkmcnt(0)
	s_nop 1
	v_add_f32_dpp v26, v26, v26 quad_perm:[2,3,0,1] row_mask:0xf bank_mask:0xf
	s_waitcnt lgkmcnt(0)
	s_nop 1
	v_add_f32_dpp v26, v26, v26 row_half_mirror row_mask:0xf bank_mask:0xf
	s_waitcnt lgkmcnt(0)
	s_nop 1
	v_add_f32_dpp v26, v26, v26 row_mirror row_mask:0xf bank_mask:0xf
	s_nop 1
	v_mov_b32_e32 v40, v26
	s_nop 1
	v_permlane16_swap_b32_e32 v40, v26
	s_waitcnt lgkmcnt(0)
	v_add_f32_e32 v26, v26, v40
	v_fmamk_f32 v26, v26, 0x3b800000, v244
	v_cmp_gt_f32_e32 vcc, s7, v26
	v_mul_f32_e32 v40, 0x4b800000, v26
	s_nop 0
	v_cndmask_b32_e32 v26, v26, v40, vcc
	v_rsq_f32_e32 v26, v26
	s_nop 0
	v_mul_f32_e32 v40, 0x45800000, v26
	v_cndmask_b32_e32 v26, v26, v40, vcc
	v_mul_f32_e32 v29, v29, v26
	v_mul_f32_e32 v36, v36, v26
	v_mul_f32_e32 v40, v108, v26
	v_mul_f32_e32 v41, v112, v26
	v_mul_f32_e32 v44, v28, v26
	v_mul_f32_e32 v37, v37, v26
	v_mul_f32_e32 v45, v30, v26
	v_cvt_pk_bf16_f32 v28, v40, v41
	v_cvt_pk_bf16_f32 v29, v44, v29
	v_cvt_pk_bf16_f32 v30, v36, v37
	v_add_co_u32_e32 v36, vcc, s35, v84
	v_mul_f32_e32 v26, v31, v26
	s_nop 0
	v_addc_co_u32_e32 v37, vcc, 0, v85, vcc
	v_cvt_pk_bf16_f32 v31, v45, v26
	global_store_dwordx4 v[36:37], v[28:31], off sc1
	v_mov_b32_e32 v26, v38
	s_nop 0
	v_pk_mul_f32 v[28:29], v[82:83], v[42:43]
	v_and_b32_e32 v31, 0xffff0000, v27
	v_lshlrev_b32_e32 v30, 16, v27
	v_mov_b32_e32 v27, v28
	v_pk_fma_f32 v[26:27], v[14:15], v[32:33], v[26:27]
	v_mov_b32_e32 v28, v39
	v_pk_add_f32 v[26:27], v[26:27], v[28:29]
	s_nop 0
	v_pk_mul_f32 v[26:27], v[26:27], v[30:31]
	s_nop 0
	v_pk_mul_f32 v[28:29], v[26:27], v[26:27]
	s_nop 0
	v_add_f32_e32 v28, v28, v49
	v_add_f32_e32 v28, v29, v28
	s_waitcnt lgkmcnt(0)
	s_nop 1
	v_add_f32_dpp v28, v28, v28 quad_perm:[1,0,3,2] row_mask:0xf bank_mask:0xf
	s_waitcnt lgkmcnt(0)
	s_nop 1
	v_add_f32_dpp v28, v28, v28 quad_perm:[2,3,0,1] row_mask:0xf bank_mask:0xf
	s_waitcnt lgkmcnt(0)
	s_nop 1
	v_add_f32_dpp v28, v28, v28 row_half_mirror row_mask:0xf bank_mask:0xf
	s_waitcnt lgkmcnt(0)
	s_nop 1
	v_add_f32_dpp v28, v28, v28 row_mirror row_mask:0xf bank_mask:0xf
	s_nop 1
	v_mov_b32_e32 v29, v28
	s_nop 1
	v_permlane16_swap_b32_e32 v29, v28
	s_waitcnt lgkmcnt(0)
	v_add_f32_e32 v28, v28, v29
	v_fmamk_f32 v28, v28, 0x3b800000, v244
	v_cmp_gt_f32_e32 vcc, s7, v28
	v_mul_f32_e32 v29, 0x4b800000, v28
	s_nop 0
	v_cndmask_b32_e32 v28, v28, v29, vcc
	v_rsq_f32_e32 v28, v28
	s_nop 0
	v_mul_f32_e32 v29, 0x45800000, v28
	v_cndmask_b32_e32 v28, v28, v29, vcc
	v_mul_f32_e32 v25, v25, v28
	v_mul_f32_e32 v27, v27, v28
	v_mul_f32_e32 v29, v109, v28
	v_mul_f32_e32 v30, v113, v28
	v_mul_f32_e32 v31, v24, v28
	v_mul_f32_e32 v32, v34, v28
	v_mul_f32_e32 v33, v35, v28
	v_mul_f32_e32 v34, v26, v28
	v_cvt_pk_bf16_f32 v24, v29, v30
	v_cvt_pk_bf16_f32 v25, v31, v25
	v_cvt_pk_bf16_f32 v26, v32, v33
	v_cvt_pk_bf16_f32 v27, v34, v27
	global_store_dwordx4 v[36:37], v[24:27], off offset:2048 sc1
	s_cbranch_scc1 .LBB0_227
